# pa/pd/out weight conversion moved from the scan phase to the up2 tail (balances the scan phase halves); sibling barrier: last arriver skips the poll
# speedup vs baseline: 1.0204x; 1.0015x over previous
.Llb_rel_b1:
	global_atomic_add v2, v0, v1, s[8:9] sc0
	s_mov_b32 s11, 0
	s_waitcnt vmcnt(0)
	v_readfirstlane_b32 s12, v2
	s_and_b32 s13, s12, 3
	s_or_b32 s12, s12, 3
	s_add_u32 s12, s12, 1
	s_cmp_eq_u32 s13, 3
	s_cbranch_scc1 .Llb_done_b1
